# G4 relu^2 epilogue: dropped the 128 self-max canonicalisations (MFMA results are never signalling NaNs), hazard pads re-derived
# speedup vs baseline: 1.0009x; 1.0005x over previous
.LBB0_127:
	v_lshl_add_u32 v141, s44, 8, v144
	v_lshlrev_b32_e32 v140, 1, v140
	v_lshl_add_u32 v140, v141, 13, v140
	v_max_f32_e32 v142, 0, v126
	v_max_f32_e32 v148, 0, v122
	v_max_f32_e32 v143, 0, v127
	v_max_f32_e32 v149, 0, v123
	v_max_f32_e32 v152, 0, v128
	v_max_f32_e32 v154, 0, v124
	v_max_f32_e32 v153, 0, v129
	v_pk_mul_f32 v[142:143], v[142:143], v[142:143]
	v_max_f32_e32 v155, 0, v125
	v_pk_mul_f32 v[148:149], v[148:149], v[148:149]
	v_pk_mul_f32 v[156:157], v[152:153], v[152:153]
	v_cvt_pk_bf16_f32 v152, v142, v143
	v_max_f32_e32 v142, 0, v94
	v_pk_mul_f32 v[158:159], v[154:155], v[154:155]
	v_cvt_pk_bf16_f32 v154, v148, v149
	v_max_f32_e32 v148, 0, v90
	v_max_f32_e32 v143, 0, v95
	v_cvt_pk_bf16_f32 v153, v156, v157
	v_cvt_pk_bf16_f32 v155, v158, v159
	v_max_f32_e32 v149, 0, v91
	global_store_dwordx4 v140, v[152:155], s[46:47]
	v_pk_mul_f32 v[142:143], v[142:143], v[142:143]
	v_pk_mul_f32 v[148:149], v[148:149], v[148:149]
	v_max_f32_e32 v152, 0, v96
	v_max_f32_e32 v154, 0, v92
	v_max_f32_e32 v153, 0, v97
	v_max_f32_e32 v155, 0, v93
	v_pk_mul_f32 v[156:157], v[152:153], v[152:153]
	v_pk_mul_f32 v[158:159], v[154:155], v[154:155]
	v_cvt_pk_bf16_f32 v152, v142, v143
	v_cvt_pk_bf16_f32 v153, v156, v157
	v_cvt_pk_bf16_f32 v154, v148, v149
	v_cvt_pk_bf16_f32 v155, v158, v159
	global_store_dwordx4 v140, v[152:155], s[46:47] offset:256
	s_nop 0
	v_max_f32_e32 v148, 0, v114
	v_max_f32_e32 v154, 0, v116
	v_max_f32_e32 v142, 0, v118
	v_max_f32_e32 v143, 0, v119
	v_max_f32_e32 v149, 0, v115
	v_max_f32_e32 v152, 0, v120
	v_max_f32_e32 v153, 0, v121
	v_max_f32_e32 v155, 0, v117
	v_pk_mul_f32 v[142:143], v[142:143], v[142:143]
	v_pk_mul_f32 v[148:149], v[148:149], v[148:149]
	v_pk_mul_f32 v[156:157], v[152:153], v[152:153]
	v_pk_mul_f32 v[158:159], v[154:155], v[154:155]
	v_add_u32_e32 v141, 0x20000, v140
	v_cvt_pk_bf16_f32 v152, v142, v143
	v_cvt_pk_bf16_f32 v153, v156, v157
	v_cvt_pk_bf16_f32 v154, v148, v149
	v_cvt_pk_bf16_f32 v155, v158, v159
	global_store_dwordx4 v141, v[152:155], s[46:47]
	s_nop 0
	v_max_f32_e32 v148, 0, v82
	v_max_f32_e32 v154, 0, v84
	v_max_f32_e32 v142, 0, v86
	v_max_f32_e32 v143, 0, v87
	v_max_f32_e32 v149, 0, v83
	v_max_f32_e32 v152, 0, v88
	v_max_f32_e32 v153, 0, v89
	v_max_f32_e32 v155, 0, v85
	v_pk_mul_f32 v[142:143], v[142:143], v[142:143]
	v_pk_mul_f32 v[148:149], v[148:149], v[148:149]
	v_pk_mul_f32 v[156:157], v[152:153], v[152:153]
	v_pk_mul_f32 v[158:159], v[154:155], v[154:155]
	v_cvt_pk_bf16_f32 v152, v142, v143
	v_cvt_pk_bf16_f32 v153, v156, v157
	v_cvt_pk_bf16_f32 v154, v148, v149
	v_cvt_pk_bf16_f32 v155, v158, v159
	global_store_dwordx4 v141, v[152:155], s[46:47] offset:256
	s_nop 0
	v_max_f32_e32 v148, 0, v106
	v_max_f32_e32 v154, 0, v108
	v_max_f32_e32 v142, 0, v110
	v_max_f32_e32 v143, 0, v111
	v_max_f32_e32 v149, 0, v107
	v_max_f32_e32 v152, 0, v112
	v_max_f32_e32 v153, 0, v113
	v_max_f32_e32 v155, 0, v109
	v_pk_mul_f32 v[142:143], v[142:143], v[142:143]
	v_pk_mul_f32 v[148:149], v[148:149], v[148:149]
	v_pk_mul_f32 v[156:157], v[152:153], v[152:153]
	v_pk_mul_f32 v[158:159], v[154:155], v[154:155]
	v_add_u32_e32 v141, 0x40000, v140
	v_cvt_pk_bf16_f32 v152, v142, v143
	v_cvt_pk_bf16_f32 v153, v156, v157
	v_cvt_pk_bf16_f32 v154, v148, v149
	v_cvt_pk_bf16_f32 v155, v158, v159
	global_store_dwordx4 v141, v[152:155], s[46:47]
	s_nop 0
	v_max_f32_e32 v148, 0, v74
	v_max_f32_e32 v154, 0, v76
	v_max_f32_e32 v142, 0, v78
	v_max_f32_e32 v143, 0, v79
	v_max_f32_e32 v149, 0, v75
	v_max_f32_e32 v152, 0, v80
	v_max_f32_e32 v153, 0, v81
	v_max_f32_e32 v155, 0, v77
	v_pk_mul_f32 v[142:143], v[142:143], v[142:143]
	v_pk_mul_f32 v[148:149], v[148:149], v[148:149]
	v_pk_mul_f32 v[156:157], v[152:153], v[152:153]
	v_pk_mul_f32 v[158:159], v[154:155], v[154:155]
	v_cvt_pk_bf16_f32 v152, v142, v143
	v_cvt_pk_bf16_f32 v153, v156, v157
	v_cvt_pk_bf16_f32 v154, v148, v149
	v_cvt_pk_bf16_f32 v155, v158, v159
	global_store_dwordx4 v141, v[152:155], s[46:47] offset:256
	s_nop 0
	v_max_f32_e32 v148, 0, v98
	v_max_f32_e32 v154, 0, v100
	v_max_f32_e32 v142, 0, v102
	v_max_f32_e32 v143, 0, v103
	v_max_f32_e32 v149, 0, v99
	v_max_f32_e32 v152, 0, v104
	v_max_f32_e32 v153, 0, v105
	v_max_f32_e32 v155, 0, v101
	v_pk_mul_f32 v[142:143], v[142:143], v[142:143]
	v_pk_mul_f32 v[148:149], v[148:149], v[148:149]
	v_pk_mul_f32 v[156:157], v[152:153], v[152:153]
	v_pk_mul_f32 v[158:159], v[154:155], v[154:155]
	v_add_u32_e32 v141, 0x60000, v140
	v_cvt_pk_bf16_f32 v152, v142, v143
	v_cvt_pk_bf16_f32 v153, v156, v157
	v_cvt_pk_bf16_f32 v154, v148, v149
	v_cvt_pk_bf16_f32 v155, v158, v159
	global_store_dwordx4 v141, v[152:155], s[46:47]
	s_nop 0
	v_max_f32_e32 v148, 0, v66
	v_max_f32_e32 v154, 0, v68
	v_max_f32_e32 v142, 0, v70
	v_max_f32_e32 v143, 0, v71
	v_max_f32_e32 v149, 0, v67
	v_max_f32_e32 v152, 0, v72
	v_max_f32_e32 v153, 0, v73
	v_max_f32_e32 v155, 0, v69
	v_pk_mul_f32 v[142:143], v[142:143], v[142:143]
	v_pk_mul_f32 v[148:149], v[148:149], v[148:149]
	v_pk_mul_f32 v[156:157], v[152:153], v[152:153]
	v_pk_mul_f32 v[158:159], v[154:155], v[154:155]
	v_cvt_pk_bf16_f32 v152, v142, v143
	v_cvt_pk_bf16_f32 v153, v156, v157
	v_cvt_pk_bf16_f32 v154, v148, v149
	v_cvt_pk_bf16_f32 v155, v158, v159
	global_store_dwordx4 v141, v[152:155], s[46:47] offset:256
	s_nop 0
	v_max_f32_e32 v148, 0, v58
	v_max_f32_e32 v154, 0, v60
	v_max_f32_e32 v142, 0, v62
	v_max_f32_e32 v143, 0, v63
	v_max_f32_e32 v149, 0, v59
	v_max_f32_e32 v152, 0, v64
	v_max_f32_e32 v153, 0, v65
	v_max_f32_e32 v155, 0, v61
	v_pk_mul_f32 v[142:143], v[142:143], v[142:143]
	v_pk_mul_f32 v[148:149], v[148:149], v[148:149]
	v_pk_mul_f32 v[156:157], v[152:153], v[152:153]
	v_pk_mul_f32 v[158:159], v[154:155], v[154:155]
	v_add_u32_e32 v141, 0x100000, v140
	v_cvt_pk_bf16_f32 v152, v142, v143
	v_cvt_pk_bf16_f32 v153, v156, v157
	v_cvt_pk_bf16_f32 v154, v148, v149
	v_cvt_pk_bf16_f32 v155, v158, v159
	global_store_dwordx4 v141, v[152:155], s[46:47]
	s_nop 0
	v_max_f32_e32 v148, 0, v26
	v_max_f32_e32 v154, 0, v28
	v_max_f32_e32 v142, 0, v30
	v_max_f32_e32 v143, 0, v31
	v_max_f32_e32 v149, 0, v27
	v_max_f32_e32 v152, 0, v32
	v_max_f32_e32 v153, 0, v33
	v_max_f32_e32 v155, 0, v29
	v_pk_mul_f32 v[142:143], v[142:143], v[142:143]
	v_pk_mul_f32 v[148:149], v[148:149], v[148:149]
	v_pk_mul_f32 v[156:157], v[152:153], v[152:153]
	v_pk_mul_f32 v[158:159], v[154:155], v[154:155]
	v_cvt_pk_bf16_f32 v152, v142, v143
	v_cvt_pk_bf16_f32 v153, v156, v157
	v_cvt_pk_bf16_f32 v154, v148, v149
	v_cvt_pk_bf16_f32 v155, v158, v159
	global_store_dwordx4 v141, v[152:155], s[46:47] offset:256
	s_nop 0
	v_max_f32_e32 v148, 0, v50
	v_max_f32_e32 v154, 0, v52
	v_max_f32_e32 v142, 0, v54
	v_max_f32_e32 v143, 0, v55
	v_max_f32_e32 v149, 0, v51
	v_max_f32_e32 v152, 0, v56
	v_max_f32_e32 v153, 0, v57
	v_max_f32_e32 v155, 0, v53
	v_pk_mul_f32 v[142:143], v[142:143], v[142:143]
	v_pk_mul_f32 v[148:149], v[148:149], v[148:149]
	v_pk_mul_f32 v[156:157], v[152:153], v[152:153]
	v_pk_mul_f32 v[158:159], v[154:155], v[154:155]
	v_add_u32_e32 v141, 0x120000, v140
	v_cvt_pk_bf16_f32 v152, v142, v143
	v_cvt_pk_bf16_f32 v153, v156, v157
	v_cvt_pk_bf16_f32 v154, v148, v149
	v_cvt_pk_bf16_f32 v155, v158, v159
	global_store_dwordx4 v141, v[152:155], s[46:47]
	s_nop 0
	v_max_f32_e32 v148, 0, v18
	v_max_f32_e32 v154, 0, v20
	v_max_f32_e32 v142, 0, v22
	v_max_f32_e32 v143, 0, v23
	v_max_f32_e32 v149, 0, v19
	v_max_f32_e32 v152, 0, v24
	v_max_f32_e32 v153, 0, v25
	v_max_f32_e32 v155, 0, v21
	v_pk_mul_f32 v[142:143], v[142:143], v[142:143]
	v_pk_mul_f32 v[148:149], v[148:149], v[148:149]
	v_pk_mul_f32 v[156:157], v[152:153], v[152:153]
	v_pk_mul_f32 v[158:159], v[154:155], v[154:155]
	v_cvt_pk_bf16_f32 v152, v142, v143
	v_cvt_pk_bf16_f32 v153, v156, v157
	v_cvt_pk_bf16_f32 v154, v148, v149
	v_cvt_pk_bf16_f32 v155, v158, v159
	global_store_dwordx4 v141, v[152:155], s[46:47] offset:256
	s_nop 0
	v_max_f32_e32 v148, 0, v42
	v_max_f32_e32 v154, 0, v44
	v_max_f32_e32 v142, 0, v46
	v_max_f32_e32 v143, 0, v47
	v_max_f32_e32 v149, 0, v43
	v_max_f32_e32 v152, 0, v48
	v_max_f32_e32 v153, 0, v49
	v_max_f32_e32 v155, 0, v45
	v_pk_mul_f32 v[142:143], v[142:143], v[142:143]
	v_pk_mul_f32 v[148:149], v[148:149], v[148:149]
	v_pk_mul_f32 v[156:157], v[152:153], v[152:153]
	v_pk_mul_f32 v[158:159], v[154:155], v[154:155]
	v_add_u32_e32 v141, 0x140000, v140
	v_cvt_pk_bf16_f32 v152, v142, v143
	v_cvt_pk_bf16_f32 v153, v156, v157
	v_cvt_pk_bf16_f32 v154, v148, v149
	v_cvt_pk_bf16_f32 v155, v158, v159
	global_store_dwordx4 v141, v[152:155], s[46:47]
	s_nop 0
	v_max_f32_e32 v148, 0, v10
	v_max_f32_e32 v154, 0, v12
	v_max_f32_e32 v142, 0, v14
	v_max_f32_e32 v143, 0, v15
	v_max_f32_e32 v149, 0, v11
	v_max_f32_e32 v152, 0, v16
	v_max_f32_e32 v153, 0, v17
	v_max_f32_e32 v155, 0, v13
	v_pk_mul_f32 v[142:143], v[142:143], v[142:143]
	v_pk_mul_f32 v[148:149], v[148:149], v[148:149]
	v_pk_mul_f32 v[156:157], v[152:153], v[152:153]
	v_pk_mul_f32 v[158:159], v[154:155], v[154:155]
	v_cvt_pk_bf16_f32 v152, v142, v143
	v_cvt_pk_bf16_f32 v153, v156, v157
	v_cvt_pk_bf16_f32 v154, v148, v149
	v_cvt_pk_bf16_f32 v155, v158, v159
	global_store_dwordx4 v141, v[152:155], s[46:47] offset:256
	s_nop 1
	v_add_u32_e32 v154, 0x160000, v140
	v_max_f32_e32 v142, 0, v34
	v_max_f32_e32 v152, 0, v36
	v_max_f32_e32 v140, 0, v38
	v_max_f32_e32 v141, 0, v39
	v_max_f32_e32 v143, 0, v35
	v_max_f32_e32 v148, 0, v40
	v_max_f32_e32 v149, 0, v41
	v_max_f32_e32 v153, 0, v37
	v_pk_mul_f32 v[140:141], v[140:141], v[140:141]
	v_pk_mul_f32 v[142:143], v[142:143], v[142:143]
	v_pk_mul_f32 v[148:149], v[148:149], v[148:149]
	v_pk_mul_f32 v[152:153], v[152:153], v[152:153]
	v_cvt_pk_bf16_f32 v140, v140, v141
	v_cvt_pk_bf16_f32 v141, v148, v149
	v_cvt_pk_bf16_f32 v142, v142, v143
	v_cvt_pk_bf16_f32 v143, v152, v153
	global_store_dwordx4 v154, v[140:143], s[46:47]
	s_nop 1
	v_max_f32_e32 v142, 0, v2
	v_max_f32_e32 v152, 0, v4
	v_max_f32_e32 v140, 0, v6
	v_max_f32_e32 v141, 0, v7
	v_max_f32_e32 v143, 0, v3
	v_max_f32_e32 v148, 0, v8
	v_max_f32_e32 v149, 0, v9
	v_max_f32_e32 v153, 0, v5
	v_pk_mul_f32 v[140:141], v[140:141], v[140:141]
	v_pk_mul_f32 v[142:143], v[142:143], v[142:143]
	v_pk_mul_f32 v[148:149], v[148:149], v[148:149]
	v_pk_mul_f32 v[152:153], v[152:153], v[152:153]
	v_cvt_pk_bf16_f32 v140, v140, v141
	v_cvt_pk_bf16_f32 v141, v148, v149
	v_cvt_pk_bf16_f32 v142, v142, v143
	v_cvt_pk_bf16_f32 v143, v152, v153
	global_store_dwordx4 v154, v[140:143], s[46:47] offset:256
